# stagger
# speedup vs baseline: 1.0105x; 1.0105x over previous
.LBB0_417:
	s_mov_b32 s22, 0x80
	s_mov_b32 s23, 0
	v_lshl_add_u64 v[124:125], v[50:51], 0, s[22:23]
	v_lshl_add_u64 v[126:127], v[52:53], 0, s[22:23]
	global_load_dwordx4 v[84:87], v[124:125], off
	global_load_dwordx4 v[80:83], v[124:125], off offset:16
	global_load_dwordx4 v[76:79], v[126:127], off
	global_load_dwordx4 v[72:75], v[126:127], off offset:16
	s_waitcnt vmcnt(4) lgkmcnt(0)
	s_barrier
	ds_write_b128 v57, v[46:49]
	ds_write_b128 v57, v[42:45] offset:16
	ds_write_b128 v57, v[38:41] offset:20480
	ds_write_b128 v57, v[34:37] offset:20496
	s_waitcnt lgkmcnt(0)
	s_mov_b32 s22, 0x100
	v_lshl_add_u64 v[124:125], v[50:51], 0, s[22:23]
	v_lshl_add_u64 v[126:127], v[52:53], 0, s[22:23]
	global_load_dwordx4 v[46:49], v[124:125], off
	global_load_dwordx4 v[42:45], v[124:125], off offset:16
	global_load_dwordx4 v[38:41], v[126:127], off
	global_load_dwordx4 v[34:37], v[126:127], off offset:16
	s_barrier
	s_mov_b32 s6, 0
	s_waitcnt vmcnt(4)
	ds_write_b128 v57, v[84:87] offset:40960
	ds_write_b128 v57, v[80:83] offset:40976
	ds_write_b128 v57, v[76:79] offset:61440
	ds_write_b128 v57, v[72:75] offset:61456
	ds_read_b128 v[60:63], v59 offset:20480
	ds_read_b128 v[64:67], v58
	ds_read_b128 v[68:71], v59 offset:23040
	ds_read_b128 v[88:91], v58 offset:2560
	ds_read_b128 v[92:95], v58 offset:5120
	ds_read_b128 v[96:99], v58 offset:7680
	ds_read_b128 v[100:103], v59 offset:20544
	ds_read_b128 v[104:107], v58 offset:64
	ds_read_b128 v[108:111], v59 offset:23104
	ds_read_b128 v[112:115], v58 offset:2624
	ds_read_b128 v[116:119], v58 offset:5184
	ds_read_b128 v[120:123], v58 offset:7744
	s_add_i32 s14, s6, 3
	s_add_i32 s22, s64, -1
	s_min_u32 s14, s14, s22
	s_lshl_b32 s22, s14, 7
	s_waitcnt lgkmcnt(12)
	v_lshl_add_u64 v[124:125], v[50:51], 0, s[22:23]
	v_lshl_add_u64 v[126:127], v[52:53], 0, s[22:23]
	global_load_dwordx4 v[84:87], v[124:125], off
	global_load_dwordx4 v[80:83], v[124:125], off offset:16
	global_load_dwordx4 v[76:79], v[126:127], off
	global_load_dwordx4 v[72:75], v[126:127], off offset:16
	s_waitcnt lgkmcnt(0)
	s_barrier
	v_readfirstlane_b32 s14, v167
	s_lshr_b32 s14, s14, 8
	s_cmp_lg_u32 s14, 0
	s_cbranch_scc1 .Lsrt_loop_b
.Lsrt_loop:
	s_waitcnt vmcnt(4)
	ds_write_b128 v57, v[46:49]
	ds_write_b128 v57, v[42:45] offset:16
	ds_write_b128 v57, v[38:41] offset:20480
	ds_write_b128 v57, v[34:37] offset:20496
	ds_read_b128 v[176:179], v59 offset:61440
	ds_read_b128 v[180:183], v58 offset:40960
	ds_read_b128 v[184:187], v59 offset:64000
	ds_read_b128 v[188:191], v58 offset:43520
	ds_read_b128 v[192:195], v58 offset:46080
	ds_read_b128 v[196:199], v58 offset:48640
	ds_read_b128 v[200:203], v59 offset:61504
	ds_read_b128 v[204:207], v58 offset:41024
	ds_read_b128 v[208:211], v59 offset:64064
	ds_read_b128 v[224:227], v58 offset:43584
	ds_read_b128 v[228:231], v58 offset:46144
	ds_read_b128 v[232:235], v58 offset:48704
	s_add_i32 s14, s6, 4
	s_add_i32 s22, s64, -1
	s_min_u32 s14, s14, s22
	s_lshl_b32 s22, s14, 7
	v_mfma_f32_16x16x32_bf16 v[30:33], v[60:63], v[64:67], v[30:33]
	v_mfma_f32_16x16x32_bf16 v[14:17], v[68:71], v[64:67], v[14:17]
	v_mfma_f32_16x16x32_bf16 v[26:29], v[60:63], v[88:91], v[26:29]
	v_mfma_f32_16x16x32_bf16 v[10:13], v[68:71], v[88:91], v[10:13]
	v_mfma_f32_16x16x32_bf16 v[22:25], v[60:63], v[92:95], v[22:25]
	v_mfma_f32_16x16x32_bf16 v[6:9], v[68:71], v[92:95], v[6:9]
	v_mfma_f32_16x16x32_bf16 v[18:21], v[60:63], v[96:99], v[18:21]
	v_mfma_f32_16x16x32_bf16 v[2:5], v[68:71], v[96:99], v[2:5]
	s_waitcnt lgkmcnt(12)
	v_lshl_add_u64 v[124:125], v[50:51], 0, s[22:23]
	v_lshl_add_u64 v[126:127], v[52:53], 0, s[22:23]
	global_load_dwordx4 v[46:49], v[124:125], off
	global_load_dwordx4 v[42:45], v[124:125], off offset:16
	global_load_dwordx4 v[38:41], v[126:127], off
	global_load_dwordx4 v[34:37], v[126:127], off offset:16
	v_mfma_f32_16x16x32_bf16 v[30:33], v[100:103], v[104:107], v[30:33]
	v_mfma_f32_16x16x32_bf16 v[14:17], v[108:111], v[104:107], v[14:17]
	v_mfma_f32_16x16x32_bf16 v[26:29], v[100:103], v[112:115], v[26:29]
	v_mfma_f32_16x16x32_bf16 v[10:13], v[108:111], v[112:115], v[10:13]
	v_mfma_f32_16x16x32_bf16 v[22:25], v[100:103], v[116:119], v[22:25]
	v_mfma_f32_16x16x32_bf16 v[6:9], v[108:111], v[116:119], v[6:9]
	v_mfma_f32_16x16x32_bf16 v[18:21], v[100:103], v[120:123], v[18:21]
	v_mfma_f32_16x16x32_bf16 v[2:5], v[108:111], v[120:123], v[2:5]
	s_waitcnt lgkmcnt(0)
	s_barrier
	s_waitcnt vmcnt(4)
	ds_write_b128 v57, v[84:87] offset:40960
	ds_write_b128 v57, v[80:83] offset:40976
	ds_write_b128 v57, v[76:79] offset:61440
	ds_write_b128 v57, v[72:75] offset:61456
	ds_read_b128 v[60:63], v59 offset:20480
	ds_read_b128 v[64:67], v58
	ds_read_b128 v[68:71], v59 offset:23040
	ds_read_b128 v[88:91], v58 offset:2560
	ds_read_b128 v[92:95], v58 offset:5120
	ds_read_b128 v[96:99], v58 offset:7680
	ds_read_b128 v[100:103], v59 offset:20544
	ds_read_b128 v[104:107], v58 offset:64
	ds_read_b128 v[108:111], v59 offset:23104
	ds_read_b128 v[112:115], v58 offset:2624
	ds_read_b128 v[116:119], v58 offset:5184
	ds_read_b128 v[120:123], v58 offset:7744
	s_add_i32 s14, s6, 5
	s_add_i32 s22, s64, -1
	s_min_u32 s14, s14, s22
	s_lshl_b32 s22, s14, 7
	v_mfma_f32_16x16x32_bf16 v[30:33], v[176:179], v[180:183], v[30:33]
	v_mfma_f32_16x16x32_bf16 v[14:17], v[184:187], v[180:183], v[14:17]
	v_mfma_f32_16x16x32_bf16 v[26:29], v[176:179], v[188:191], v[26:29]
	v_mfma_f32_16x16x32_bf16 v[10:13], v[184:187], v[188:191], v[10:13]
	v_mfma_f32_16x16x32_bf16 v[22:25], v[176:179], v[192:195], v[22:25]
	v_mfma_f32_16x16x32_bf16 v[6:9], v[184:187], v[192:195], v[6:9]
	v_mfma_f32_16x16x32_bf16 v[18:21], v[176:179], v[196:199], v[18:21]
	v_mfma_f32_16x16x32_bf16 v[2:5], v[184:187], v[196:199], v[2:5]
	s_waitcnt lgkmcnt(12)
	v_lshl_add_u64 v[124:125], v[50:51], 0, s[22:23]
	v_lshl_add_u64 v[126:127], v[52:53], 0, s[22:23]
	global_load_dwordx4 v[84:87], v[124:125], off
	global_load_dwordx4 v[80:83], v[124:125], off offset:16
	global_load_dwordx4 v[76:79], v[126:127], off
	global_load_dwordx4 v[72:75], v[126:127], off offset:16
	v_mfma_f32_16x16x32_bf16 v[30:33], v[200:203], v[204:207], v[30:33]
	v_mfma_f32_16x16x32_bf16 v[14:17], v[208:211], v[204:207], v[14:17]
	v_mfma_f32_16x16x32_bf16 v[26:29], v[200:203], v[224:227], v[26:29]
	v_mfma_f32_16x16x32_bf16 v[10:13], v[208:211], v[224:227], v[10:13]
	v_mfma_f32_16x16x32_bf16 v[22:25], v[200:203], v[228:231], v[22:25]
	v_mfma_f32_16x16x32_bf16 v[6:9], v[208:211], v[228:231], v[6:9]
	v_mfma_f32_16x16x32_bf16 v[18:21], v[200:203], v[232:235], v[18:21]
	v_mfma_f32_16x16x32_bf16 v[2:5], v[208:211], v[232:235], v[2:5]
	s_waitcnt lgkmcnt(0)
	s_barrier
	s_add_i32 s6, s6, 2
	s_cmp_lt_u32 s6, s64
	s_cbranch_scc1 .Lsrt_loop
	s_branch .Lsrt_done
.Lsrt_loop_b:
	v_mfma_f32_16x16x32_bf16 v[30:33], v[60:63], v[64:67], v[30:33]
	v_mfma_f32_16x16x32_bf16 v[14:17], v[68:71], v[64:67], v[14:17]
	v_mfma_f32_16x16x32_bf16 v[26:29], v[60:63], v[88:91], v[26:29]
	v_mfma_f32_16x16x32_bf16 v[10:13], v[68:71], v[88:91], v[10:13]
	v_mfma_f32_16x16x32_bf16 v[22:25], v[60:63], v[92:95], v[22:25]
	v_mfma_f32_16x16x32_bf16 v[6:9], v[68:71], v[92:95], v[6:9]
	v_mfma_f32_16x16x32_bf16 v[18:21], v[60:63], v[96:99], v[18:21]
	v_mfma_f32_16x16x32_bf16 v[2:5], v[68:71], v[96:99], v[2:5]
	v_mfma_f32_16x16x32_bf16 v[30:33], v[100:103], v[104:107], v[30:33]
	v_mfma_f32_16x16x32_bf16 v[14:17], v[108:111], v[104:107], v[14:17]
	v_mfma_f32_16x16x32_bf16 v[26:29], v[100:103], v[112:115], v[26:29]
	v_mfma_f32_16x16x32_bf16 v[10:13], v[108:111], v[112:115], v[10:13]
	v_mfma_f32_16x16x32_bf16 v[22:25], v[100:103], v[116:119], v[22:25]
	v_mfma_f32_16x16x32_bf16 v[6:9], v[108:111], v[116:119], v[6:9]
	v_mfma_f32_16x16x32_bf16 v[18:21], v[100:103], v[120:123], v[18:21]
	v_mfma_f32_16x16x32_bf16 v[2:5], v[108:111], v[120:123], v[2:5]
	s_waitcnt vmcnt(4)
	ds_write_b128 v57, v[46:49]
	ds_write_b128 v57, v[42:45] offset:16
	ds_write_b128 v57, v[38:41] offset:20480
	ds_write_b128 v57, v[34:37] offset:20496
	ds_read_b128 v[176:179], v59 offset:61440
	ds_read_b128 v[180:183], v58 offset:40960
	ds_read_b128 v[184:187], v59 offset:64000
	ds_read_b128 v[188:191], v58 offset:43520
	ds_read_b128 v[192:195], v58 offset:46080
	ds_read_b128 v[196:199], v58 offset:48640
	ds_read_b128 v[200:203], v59 offset:61504
	ds_read_b128 v[204:207], v58 offset:41024
	ds_read_b128 v[208:211], v59 offset:64064
	ds_read_b128 v[224:227], v58 offset:43584
	ds_read_b128 v[228:231], v58 offset:46144
	ds_read_b128 v[232:235], v58 offset:48704
	s_add_i32 s14, s6, 4
	s_add_i32 s22, s64, -1
	s_min_u32 s14, s14, s22
	s_lshl_b32 s22, s14, 7
	s_waitcnt lgkmcnt(12)
	v_lshl_add_u64 v[124:125], v[50:51], 0, s[22:23]
	v_lshl_add_u64 v[126:127], v[52:53], 0, s[22:23]
	global_load_dwordx4 v[46:49], v[124:125], off
	global_load_dwordx4 v[42:45], v[124:125], off offset:16
	global_load_dwordx4 v[38:41], v[126:127], off
	global_load_dwordx4 v[34:37], v[126:127], off offset:16
	s_waitcnt lgkmcnt(0)
	s_barrier
	v_mfma_f32_16x16x32_bf16 v[30:33], v[176:179], v[180:183], v[30:33]
	v_mfma_f32_16x16x32_bf16 v[14:17], v[184:187], v[180:183], v[14:17]
	v_mfma_f32_16x16x32_bf16 v[26:29], v[176:179], v[188:191], v[26:29]
	v_mfma_f32_16x16x32_bf16 v[10:13], v[184:187], v[188:191], v[10:13]
	v_mfma_f32_16x16x32_bf16 v[22:25], v[176:179], v[192:195], v[22:25]
	v_mfma_f32_16x16x32_bf16 v[6:9], v[184:187], v[192:195], v[6:9]
	v_mfma_f32_16x16x32_bf16 v[18:21], v[176:179], v[196:199], v[18:21]
	v_mfma_f32_16x16x32_bf16 v[2:5], v[184:187], v[196:199], v[2:5]
	v_mfma_f32_16x16x32_bf16 v[30:33], v[200:203], v[204:207], v[30:33]
	v_mfma_f32_16x16x32_bf16 v[14:17], v[208:211], v[204:207], v[14:17]
	v_mfma_f32_16x16x32_bf16 v[26:29], v[200:203], v[224:227], v[26:29]
	v_mfma_f32_16x16x32_bf16 v[10:13], v[208:211], v[224:227], v[10:13]
	v_mfma_f32_16x16x32_bf16 v[22:25], v[200:203], v[228:231], v[22:25]
	v_mfma_f32_16x16x32_bf16 v[6:9], v[208:211], v[228:231], v[6:9]
	v_mfma_f32_16x16x32_bf16 v[18:21], v[200:203], v[232:235], v[18:21]
	v_mfma_f32_16x16x32_bf16 v[2:5], v[208:211], v[232:235], v[2:5]
	s_waitcnt vmcnt(4)
	ds_write_b128 v57, v[84:87] offset:40960
	ds_write_b128 v57, v[80:83] offset:40976
	ds_write_b128 v57, v[76:79] offset:61440
	ds_write_b128 v57, v[72:75] offset:61456
	ds_read_b128 v[60:63], v59 offset:20480
	ds_read_b128 v[64:67], v58
	ds_read_b128 v[68:71], v59 offset:23040
	ds_read_b128 v[88:91], v58 offset:2560
	ds_read_b128 v[92:95], v58 offset:5120
	ds_read_b128 v[96:99], v58 offset:7680
	ds_read_b128 v[100:103], v59 offset:20544
	ds_read_b128 v[104:107], v58 offset:64
	ds_read_b128 v[108:111], v59 offset:23104
	ds_read_b128 v[112:115], v58 offset:2624
	ds_read_b128 v[116:119], v58 offset:5184
	ds_read_b128 v[120:123], v58 offset:7744
	s_add_i32 s14, s6, 5
	s_add_i32 s22, s64, -1
	s_min_u32 s14, s14, s22
	s_lshl_b32 s22, s14, 7
	s_waitcnt lgkmcnt(12)
	v_lshl_add_u64 v[124:125], v[50:51], 0, s[22:23]
	v_lshl_add_u64 v[126:127], v[52:53], 0, s[22:23]
	global_load_dwordx4 v[84:87], v[124:125], off
	global_load_dwordx4 v[80:83], v[124:125], off offset:16
	global_load_dwordx4 v[76:79], v[126:127], off
	global_load_dwordx4 v[72:75], v[126:127], off offset:16
	s_waitcnt lgkmcnt(0)
	s_barrier
	s_add_i32 s6, s6, 2
	s_cmp_lt_u32 s6, s64
	s_cbranch_scc1 .Lsrt_loop_b
.Lsrt_done:
	s_waitcnt vmcnt(0)
.LBB0_419:
	s_cmp_eq_u64 s[24:25], 0
	s_cselect_b64 vcc, -1, 0
	s_ashr_i32 s0, s0, 3
	s_waitcnt vmcnt(0)
	v_add_u32_e32 v34, s9, v56
	s_add_i32 s0, s0, 1
	v_or_b32_e32 v44, v34, v55
	s_mul_hi_i32 s6, s0, 0x12000
	s_mul_i32 s0, s0, 0x12000
	v_or_b32_e32 v34, s1, v0
	v_ashrrev_i32_e32 v45, 31, v44
	s_add_u32 s0, s62, s0
	v_lshl_or_b32 v60, v54, 2, v34
	v_lshlrev_b64 v[34:35], 11, v[44:45]
	s_addc_u32 s6, s63, s6
	s_lshl_b32 s1, s1, 2
	v_or_b32_e32 v36, v34, v60
	v_mov_b32_e32 v37, v35
	v_readlane_b32 s22, v252, 35
	s_add_u32 s0, s0, s1
	v_lshlrev_b64 v[36:37], 2, v[36:37]
	v_readlane_b32 s23, v252, 36
	s_addc_u32 s1, s6, 0
	v_lshlrev_b32_e32 v0, 2, v0
	v_lshl_add_u64 v[46:47], s[22:23], 0, v[36:37]
	v_lshl_add_u64 v[48:49], s[24:25], 0, v[36:37]
	v_lshl_add_u64 v[36:37], s[0:1], 0, v[0:1]
	v_lshlrev_b32_e32 v0, 4, v54
	v_lshl_add_u64 v[50:51], v[36:37], 0, v[0:1]
	global_load_dwordx4 v[36:39], v[50:51], off
	global_load_dwordx4 v[40:43], v[50:51], off offset:64
	v_cndmask_b32_e32 v73, v49, v47, vcc
	v_cndmask_b32_e32 v72, v48, v46, vcc
	s_mov_b32 s6, 0x20000
	v_add_co_u32_e32 v74, vcc, s6, v72
	s_nop 1
	v_addc_co_u32_e32 v75, vcc, 0, v73, vcc
	s_mov_b32 s6, 0x40000
	v_add_co_u32_e32 v76, vcc, s6, v72
	s_nop 1
	v_addc_co_u32_e32 v77, vcc, 0, v73, vcc
	s_mov_b32 s6, 0x60000
	v_add_co_u32_e32 v78, vcc, s6, v72
	s_nop 1
	v_addc_co_u32_e32 v79, vcc, 0, v73, vcc
	v_sub_co_u32_e32 v80, vcc, v46, v72
	s_nop 1
	v_subb_co_u32_e32 v81, vcc, v47, v73, vcc
	global_load_dwordx4 v[88:91], v[72:73], off
	global_load_dwordx4 v[92:95], v[74:75], off
	global_load_dwordx4 v[96:99], v[76:77], off
	global_load_dwordx4 v[100:103], v[78:79], off
	global_load_dwordx4 v[104:107], v[72:73], off offset:64
	global_load_dwordx4 v[108:111], v[74:75], off offset:64
	global_load_dwordx4 v[112:115], v[76:77], off offset:64
	global_load_dwordx4 v[116:119], v[78:79], off offset:64
	s_waitcnt vmcnt(9)
	v_pk_mul_f32 v[38:39], v[130:131], v[38:39] op_sel_hi:[0,1]
	v_pk_mul_f32 v[36:37], v[130:131], v[36:37] op_sel_hi:[0,1]
	s_waitcnt vmcnt(7)
	v_pk_fma_f32 v[90:91], v[32:33], v[38:39], v[90:91]
	v_pk_fma_f32 v[88:89], v[30:31], v[36:37], v[88:89]
	v_lshl_add_u64 v[82:83], v[72:73], 0, v[80:81]
	global_store_dwordx4 v[82:83], v[88:91], off
	s_waitcnt vmcnt(7)
	v_pk_fma_f32 v[94:95], v[28:29], v[38:39], v[94:95]
	v_pk_fma_f32 v[92:93], v[26:27], v[36:37], v[92:93]
	v_lshl_add_u64 v[84:85], v[74:75], 0, v[80:81]
	global_store_dwordx4 v[84:85], v[92:95], off
	s_waitcnt vmcnt(7)
	v_pk_fma_f32 v[98:99], v[24:25], v[38:39], v[98:99]
	v_pk_fma_f32 v[96:97], v[22:23], v[36:37], v[96:97]
	v_lshl_add_u64 v[82:83], v[76:77], 0, v[80:81]
	global_store_dwordx4 v[82:83], v[96:99], off
	s_waitcnt vmcnt(7)
	v_pk_fma_f32 v[102:103], v[20:21], v[38:39], v[102:103]
	v_pk_fma_f32 v[100:101], v[18:19], v[36:37], v[100:101]
	v_lshl_add_u64 v[84:85], v[78:79], 0, v[80:81]
	global_store_dwordx4 v[84:85], v[100:103], off
	s_waitcnt vmcnt(12)
	v_pk_mul_f32 v[42:43], v[130:131], v[42:43] op_sel_hi:[0,1]
	v_pk_mul_f32 v[40:41], v[130:131], v[40:41] op_sel_hi:[0,1]
	s_waitcnt vmcnt(7)
	v_pk_fma_f32 v[106:107], v[16:17], v[42:43], v[106:107]
	v_pk_fma_f32 v[104:105], v[14:15], v[40:41], v[104:105]
	v_lshl_add_u64 v[82:83], v[72:73], 0, v[80:81]
	global_store_dwordx4 v[82:83], v[104:107], off offset:64
	s_waitcnt vmcnt(7)
	v_pk_fma_f32 v[110:111], v[12:13], v[42:43], v[110:111]
	v_pk_fma_f32 v[108:109], v[10:11], v[40:41], v[108:109]
	v_lshl_add_u64 v[84:85], v[74:75], 0, v[80:81]
	global_store_dwordx4 v[84:85], v[108:111], off offset:64
	s_waitcnt vmcnt(7)
	v_pk_fma_f32 v[114:115], v[8:9], v[42:43], v[114:115]
	v_pk_fma_f32 v[112:113], v[6:7], v[40:41], v[112:113]
	v_lshl_add_u64 v[82:83], v[76:77], 0, v[80:81]
	global_store_dwordx4 v[82:83], v[112:115], off offset:64
	s_waitcnt vmcnt(7)
	v_pk_fma_f32 v[118:119], v[4:5], v[42:43], v[118:119]
	v_pk_fma_f32 v[116:117], v[2:3], v[40:41], v[116:117]
	v_lshl_add_u64 v[84:85], v[78:79], 0, v[80:81]
	global_store_dwordx4 v[84:85], v[116:119], off offset:64
